# mixer first grab: workgroups 256..511 spin (bounded) on own list counter >= 32 instead of fixed 10us sleep
# baseline (speedup 1.0000x reference)
.LBB0_299:
	s_or_b64 exec, exec, s[4:5]
	v_readlane_b32 s4, v254, 57
	v_readlane_b32 s5, v254, 58
	s_lshl_b32 s90, s4, 4
	s_lshl_b64 s[4:5], s[90:91], 2
	s_add_u32 s4, s42, s4
	s_addc_u32 s5, s43, s5
	v_readlane_b32 s6, v254, 29
	s_add_u32 s6, s4, s6
	s_addc_u32 s7, s5, 0
	v_writelane_b32 v254, s6, 61
	s_barrier
	s_nop 0
	v_writelane_b32 v254, s7, 62
	s_nop 0
	v_readlane_b32 s6, v254, 31
	s_add_u32 s6, s4, s6
	s_addc_u32 s7, s5, 0
	v_writelane_b32 v254, s6, 63
	s_nop 1
	v_writelane_b32 v255, s7, 0
	v_readlane_b32 s6, v254, 33
	s_add_u32 s6, s4, s6
	s_addc_u32 s7, s5, 0
	v_writelane_b32 v255, s6, 1
	s_nop 1
	v_writelane_b32 v255, s7, 2
	v_readlane_b32 s6, v254, 35
	s_add_u32 s6, s4, s6
	s_addc_u32 s7, s5, 0
	v_writelane_b32 v255, s6, 3
	s_nop 1
	v_writelane_b32 v255, s7, 4
	v_readlane_b32 s6, v254, 37
	s_add_u32 s6, s4, s6
	s_addc_u32 s7, s5, 0
	v_writelane_b32 v255, s6, 5
	s_nop 1
	v_writelane_b32 v255, s7, 6
	v_readlane_b32 s6, v254, 39
	s_add_u32 s6, s4, s6
	s_addc_u32 s7, s5, 0
	v_writelane_b32 v255, s6, 7
	s_nop 1
	v_writelane_b32 v255, s7, 8
	v_readlane_b32 s6, v254, 41
	s_add_u32 s6, s4, s6
	s_addc_u32 s7, s5, 0
	v_writelane_b32 v255, s6, 9
	s_nop 1
	v_writelane_b32 v255, s7, 10
	v_readlane_b32 s6, v254, 43
	s_add_u32 s4, s4, s6
	s_addc_u32 s5, s5, 0
	v_writelane_b32 v255, s4, 11
	s_nop 1
	v_writelane_b32 v255, s5, 12
	v_readlane_b32 s6, v254, 13
	s_cmpk_lt_u32 s6, 0x100
	s_cbranch_scc1 .Lmx_nodelay
	v_readlane_b32 s6, v254, 61
	v_readlane_b32 s7, v254, 62
	s_movk_i32 s8, 200
	s_nop 4
.Lmx_wait:
	s_sleep 16
	global_load_dword v0, v177, s[6:7] sc1
	s_waitcnt vmcnt(0)
	v_readfirstlane_b32 s9, v0
	s_nop 0
	s_cmpk_ge_u32 s9, 32
	s_cbranch_scc1 .Lmx_nodelay
	s_add_i32 s8, s8, -1
	s_cmp_lg_u32 s8, 0
	s_cbranch_scc1 .Lmx_wait
